# k30: k20 + nontemporal hint on the norm phases' once-read residual row loads (cache-policy lever)
# speedup vs baseline: 1.0023x; 1.0014x over previous
; __device__ void norm_rows(const float* Xc, const float* Xl, bf16_t* H, const float* nw, const float* modl, int shi, int sci, int base, int r1, int step) {
;     ...
;     for (int row = base + wid * 4; row < r1; row += step) {
;         const float* xp = (row < TCTX ? Xc : Xl) + (size_t)row * 1024 + lane * 4;
;         f32x4 v[4][4]; float ss[4];
; #pragma unroll
;         for (int u = 0; u < 4; ++u)
; #pragma unroll
;             for (int q = 0; q < 4; ++q) v[u][q] = *(const f32x4*)(xp + u * 1024 + q * 256);
; #pragma unroll
;         for (int u = 0; u < 4; ++u) { float a = 0.f;
; #pragma unroll
;             for (int q = 0; q < 4; ++q) a += v[u][q][0] * v[u][q][0] + v[u][q][1] * v[u][q][1] + v[u][q][2] * v[u][q][2] + v[u][q][3] * v[u][q][3];
;             ss[u] = a; }
; #pragma unroll
;         for (int o = 32; o >= 1; o >>= 1)
; #pragma unroll
;             for (int u = 0; u < 4; ++u) ss[u] += __int_as_float(__builtin_amdgcn_ds_bpermute((lane ^ o) << 2, __float_as_int(ss[u])));
;         const int mb = row < TCTX ? 32 : (row - TCTX) >> 11;
;         const float* shp = modl + ((size_t)mb * 6 + shi) * 1024; const float* scp = modl + ((size_t)mb * 6 + sci) * 1024;
; #pragma unroll
;         for (int q = 0; q < 4; ++q) { const int c = q * 256 + lane * 4;
;             const f32x4 w = *(const f32x4*)(nw + c), sh = *(const f32x4*)(shp + c), sc = *(const f32x4*)(scp + c);
;             const f32x4 wm = w * (sc + 1.0f);
.LBB0_113:
	v_cmp_gt_i32_e64 s[2:3], s71, v70
	v_add_u32_e32 v4, 0xffffe000, v70
	v_add_co_u32_e32 v86, vcc, s36, v74
	v_cndmask_b32_e64 v3, v71, v117, s[2:3]
	v_cndmask_b32_e64 v2, v118, v119, s[2:3]
	v_ashrrev_i32_e32 v4, 11, v4
	v_addc_co_u32_e32 v87, vcc, -1, v75, vcc
	v_lshl_add_u64 v[14:15], v[2:3], 0, v[76:77]
	v_mul_i32_i24_e32 v7, 6, v4
	v_add_co_u32_e32 v6, vcc, 0x1000, v14
	v_cndmask_b32_e64 v10, v7, v211, s[2:3]
	s_nop 0
	v_addc_co_u32_e32 v7, vcc, 0, v15, vcc
	v_ashrrev_i32_e32 v11, 31, v10
	v_add_co_u32_e32 v12, vcc, s71, v14
	v_lshlrev_b64 v[16:17], 12, v[10:11]
	s_nop 0
	v_addc_co_u32_e32 v13, vcc, 0, v15, vcc
	v_lshl_add_u64 v[88:89], s[60:61], 0, v[16:17]
	global_load_dwordx4 v[66:69], v[72:73], off nt
	global_load_dwordx4 v[50:53], v[14:15], off nt
	global_load_dwordx4 v[34:37], v[14:15], off offset:1024 nt
	global_load_dwordx4 v[18:21], v[14:15], off offset:2048 nt
	global_load_dwordx4 v[2:5], v[14:15], off offset:3072 nt
	v_add_co_u32_e32 v14, vcc, 0x3000, v14
	v_lshl_add_u64 v[90:91], v[88:89], 0, s[68:69]
	s_nop 0
	v_addc_co_u32_e32 v15, vcc, 0, v15, vcc
	v_lshl_add_u64 v[92:93], v[90:91], 0, v[78:79]
	global_load_dwordx4 v[54:57], v[6:7], off nt
	global_load_dwordx4 v[38:41], v[6:7], off offset:1024 nt
	global_load_dwordx4 v[22:25], v[6:7], off offset:2048 nt
	s_nop 0
	global_load_dwordx4 v[6:9], v[6:7], off offset:3072 nt
	s_nop 0
	global_load_dwordx4 v[58:61], v[12:13], off nt
	global_load_dwordx4 v[42:45], v[12:13], off offset:1024 nt
	global_load_dwordx4 v[26:29], v[12:13], off offset:2048 nt
	s_nop 0
	global_load_dwordx4 v[10:13], v[12:13], off offset:3072 nt
	s_nop 0
	global_load_dwordx4 v[62:65], v[14:15], off nt
	global_load_dwordx4 v[46:49], v[14:15], off offset:1024 nt
	global_load_dwordx4 v[30:33], v[14:15], off offset:2048 nt
	s_nop 0
	global_load_dwordx4 v[14:17], v[14:15], off offset:3072
	v_lshl_add_u64 v[88:89], v[88:89], 0, v[78:79]
	global_load_dwordx4 v[92:95], v[92:93], off
	v_add_u32_e32 v70, s70, v70
	v_lshl_add_u64 v[76:77], v[76:77], 0, s[58:59]
	s_waitcnt vmcnt(16)
	v_mov_b32_e32 v98, v51
	s_waitcnt vmcnt(15)
	v_mov_b32_e32 v99, v35
	s_waitcnt vmcnt(14)
	v_mov_b32_e32 v106, v19
	s_waitcnt vmcnt(13)
	v_mov_b32_e32 v107, v3
	v_mov_b32_e32 v96, v50
	v_mov_b32_e32 v97, v34
	v_mov_b32_e32 v104, v18
	v_mov_b32_e32 v105, v2
	v_pk_mul_f32 v[98:99], v[98:99], v[98:99]
	v_pk_mul_f32 v[106:107], v[106:107], v[106:107]
	v_pk_fma_f32 v[96:97], v[96:97], v[96:97], v[98:99]
	v_pk_fma_f32 v[98:99], v[104:105], v[104:105], v[106:107]
	v_mov_b32_e32 v100, v52
	v_mov_b32_e32 v101, v36
	s_waitcnt vmcnt(0)
	v_pk_add_f32 v[94:95], v[94:95], 1.0 op_sel_hi:[1,0]
	v_pk_add_f32 v[106:107], v[92:93], 1.0 op_sel_hi:[1,0]
	v_pk_mul_f32 v[92:93], v[68:69], v[94:95]
	v_pk_mul_f32 v[94:95], v[66:67], v[106:107]
	v_mov_b32_e32 v106, v23
	v_mov_b32_e32 v107, v7
	v_mov_b32_e32 v108, v20
	v_mov_b32_e32 v109, v4
	v_mov_b32_e32 v120, v55
	v_mov_b32_e32 v121, v39
	v_pk_fma_f32 v[96:97], v[100:101], v[100:101], v[96:97]
	v_mov_b32_e32 v100, v22
	v_mov_b32_e32 v101, v6
	v_pk_mul_f32 v[106:107], v[106:107], v[106:107]
	v_mov_b32_e32 v102, v53
	v_mov_b32_e32 v103, v37
	v_mov_b32_e32 v104, v54
	v_mov_b32_e32 v105, v38
	v_pk_fma_f32 v[98:99], v[108:109], v[108:109], v[98:99]
	v_pk_mul_f32 v[108:109], v[120:121], v[120:121]
	v_pk_fma_f32 v[100:101], v[100:101], v[100:101], v[106:107]
	v_mov_b32_e32 v106, v59
	v_mov_b32_e32 v107, v43
	v_mov_b32_e32 v110, v21
	v_mov_b32_e32 v111, v5
	v_mov_b32_e32 v66, v56
	v_mov_b32_e32 v67, v40
	v_pk_fma_f32 v[122:123], v[102:103], v[102:103], v[96:97]
	v_mov_b32_e32 v102, v24
	v_mov_b32_e32 v103, v8
	v_pk_fma_f32 v[104:105], v[104:105], v[104:105], v[108:109]
	v_mov_b32_e32 v108, v58
	v_mov_b32_e32 v109, v42
	v_pk_mul_f32 v[106:107], v[106:107], v[106:107]
	v_pk_fma_f32 v[96:97], v[110:111], v[110:111], v[98:99]
	v_mov_b32_e32 v98, v25
	v_mov_b32_e32 v99, v9
	v_pk_fma_f32 v[66:67], v[66:67], v[66:67], v[104:105]
	v_mov_b32_e32 v104, v60
	v_mov_b32_e32 v105, v44
	v_pk_fma_f32 v[100:101], v[102:103], v[102:103], v[100:101]
	v_pk_fma_f32 v[106:107], v[108:109], v[108:109], v[106:107]
	v_mov_b32_e32 v108, v27
	v_mov_b32_e32 v109, v11
	v_pk_fma_f32 v[110:111], v[98:99], v[98:99], v[100:101]
	v_pk_fma_f32 v[100:101], v[104:105], v[104:105], v[106:107]
	v_mov_b32_e32 v104, v63
	v_mov_b32_e32 v105, v47
	v_mov_b32_e32 v68, v57
	v_mov_b32_e32 v69, v41
	v_mov_b32_e32 v102, v26
	v_mov_b32_e32 v103, v10
	v_pk_mul_f32 v[108:109], v[108:109], v[108:109]
	v_mov_b32_e32 v98, v62
	v_mov_b32_e32 v99, v46
	v_pk_mul_f32 v[104:105], v[104:105], v[104:105]
	v_pk_fma_f32 v[102:103], v[102:103], v[102:103], v[108:109]
	v_pk_fma_f32 v[66:67], v[68:69], v[68:69], v[66:67]
	v_mov_b32_e32 v68, v28
	v_mov_b32_e32 v69, v12
	v_pk_fma_f32 v[104:105], v[98:99], v[98:99], v[104:105]
	v_mov_b32_e32 v98, v31
	v_mov_b32_e32 v99, v15
	v_pk_fma_f32 v[68:69], v[68:69], v[68:69], v[102:103]
	v_mov_b32_e32 v102, v30
	v_mov_b32_e32 v103, v14
	v_pk_mul_f32 v[98:99], v[98:99], v[98:99]
	v_mov_b32_e32 v106, v64
	v_mov_b32_e32 v107, v48
	v_pk_fma_f32 v[102:103], v[102:103], v[102:103], v[98:99]
	v_mov_b32_e32 v98, v29
	v_mov_b32_e32 v99, v13
	v_pk_fma_f32 v[104:105], v[106:107], v[106:107], v[104:105]
	v_mov_b32_e32 v106, v32
	v_mov_b32_e32 v107, v16
	v_pk_fma_f32 v[98:99], v[98:99], v[98:99], v[68:69]
	v_mov_b32_e32 v68, v65
	v_mov_b32_e32 v69, v49
	v_pk_fma_f32 v[102:103], v[106:107], v[106:107], v[102:103]
	v_mov_b32_e32 v107, v122
	v_mov_b32_e32 v106, v66
	v_mov_b32_e32 v122, v67
	v_mov_b32_e32 v66, v33
	v_mov_b32_e32 v67, v17
	v_pk_fma_f32 v[104:105], v[68:69], v[68:69], v[104:105]
	v_pk_fma_f32 v[102:103], v[66:67], v[66:67], v[102:103]
	global_load_dwordx4 v[66:69], v[88:89], off
	v_mov_b32_e32 v108, v61
	v_mov_b32_e32 v109, v45
	v_pk_fma_f32 v[100:101], v[108:109], v[108:109], v[100:101]
	v_mov_b32_e32 v109, v96
	v_mov_b32_e32 v108, v110
	v_mov_b32_e32 v96, v111
	v_pk_add_f32 v[110:111], v[106:107], v[122:123]
	v_lshl_add_u64 v[106:107], v[90:91], 0, v[80:81]
	v_pk_add_f32 v[108:109], v[110:111], v[108:109]
	v_mov_b32_e32 v111, v100
	v_mov_b32_e32 v110, v104
	v_mov_b32_e32 v100, v105
	v_mov_b32_e32 v105, v98
	v_mov_b32_e32 v104, v102
	v_pk_add_f32 v[96:97], v[108:109], v[96:97]
	v_pk_add_f32 v[100:101], v[110:111], v[100:101]
	v_mov_b32_e32 v98, v103
	ds_bpermute_b32 v103, v1, v97
	ds_bpermute_b32 v102, v1, v96
	v_pk_add_f32 v[100:101], v[100:101], v[104:105]
	s_waitcnt lgkmcnt(0)
; __device__ __forceinline__ unsigned cvt_pk_bf16(float lo, float hi) { unsigned r; asm("v_cvt_pk_bf16_f32 %0, %1, %2" : "=v"(r) : "v"(lo), "v"(hi)); return r; }
; __device__ void norm_rows(const float* Xc, const float* Xl, bf16_t* H, const float* nw, const float* modl, int shi, int sci, int base, int r1, int step) {
;     ...
;         for (int o = 32; o >= 1; o >>= 1)
; #pragma unroll
;             for (int u = 0; u < 4; ++u) ss[u] += __int_as_float(__builtin_amdgcn_ds_bpermute((lane ^ o) << 2, __float_as_int(ss[u])));
;         const int mb = row < TCTX ? 32 : (row - TCTX) >> 11;
;         const float* shp = modl + ((size_t)mb * 6 + shi) * 1024; const float* scp = modl + ((size_t)mb * 6 + sci) * 1024;
; #pragma unroll
;         for (int q = 0; q < 4; ++q) { const int c = q * 256 + lane * 4;
;             const f32x4 w = *(const f32x4*)(nw + c), sh = *(const f32x4*)(shp + c), sc = *(const f32x4*)(scp + c);
;             const f32x4 wm = w * (sc + 1.0f);
; #pragma unroll
;             for (int u = 0; u < 4; ++u) { const float rstd = rsqrtf(ss[u] * (1.0f / 1024.0f) + 1e-6f);
;                 const f32x4 h = (v[u][q] * rstd) * wm + sh;
;                 u32x2 o; o.x = cvt_pk_bf16(h[0], h[1]); o.y = cvt_pk_bf16(h[2], h[3]);
;                 *(u32x2*)(H + (size_t)(row + u) * 1024 + c) = o; } }
	v_pk_add_f32 v[96:97], v[96:97], v[102:103]
	v_pk_add_f32 v[98:99], v[100:101], v[98:99]
	ds_bpermute_b32 v101, v1, v99
	ds_bpermute_b32 v100, v1, v98
	ds_bpermute_b32 v103, v112, v97
	ds_bpermute_b32 v102, v112, v96
	s_waitcnt lgkmcnt(2)
	v_pk_add_f32 v[98:99], v[98:99], v[100:101]
	ds_bpermute_b32 v101, v112, v99
	ds_bpermute_b32 v100, v112, v98
	s_waitcnt lgkmcnt(2)
	v_pk_add_f32 v[96:97], v[96:97], v[102:103]
	ds_bpermute_b32 v103, v113, v97
	ds_bpermute_b32 v102, v113, v96
	s_waitcnt lgkmcnt(2)
	v_pk_add_f32 v[98:99], v[98:99], v[100:101]
	ds_bpermute_b32 v101, v113, v99
	ds_bpermute_b32 v100, v113, v98
	s_waitcnt lgkmcnt(2)
	v_pk_add_f32 v[96:97], v[96:97], v[102:103]
	ds_bpermute_b32 v103, v114, v97
	ds_bpermute_b32 v102, v114, v96
	s_waitcnt lgkmcnt(2)
	v_pk_add_f32 v[98:99], v[98:99], v[100:101]
	ds_bpermute_b32 v101, v114, v99
	ds_bpermute_b32 v100, v114, v98
	s_waitcnt lgkmcnt(2)
	v_pk_add_f32 v[96:97], v[96:97], v[102:103]
	ds_bpermute_b32 v103, v115, v97
	ds_bpermute_b32 v102, v115, v96
	s_waitcnt lgkmcnt(2)
	v_pk_add_f32 v[98:99], v[98:99], v[100:101]
	ds_bpermute_b32 v101, v115, v99
	ds_bpermute_b32 v100, v115, v98
	s_waitcnt lgkmcnt(2)
	v_pk_add_f32 v[96:97], v[96:97], v[102:103]
	ds_bpermute_b32 v103, v116, v97
	ds_bpermute_b32 v102, v116, v96
	s_waitcnt lgkmcnt(2)
	v_pk_add_f32 v[98:99], v[98:99], v[100:101]
	ds_bpermute_b32 v101, v116, v99
	ds_bpermute_b32 v100, v116, v98
	s_waitcnt lgkmcnt(2)
	v_pk_add_f32 v[96:97], v[96:97], v[102:103]
	s_waitcnt lgkmcnt(0)
	v_pk_add_f32 v[98:99], v[98:99], v[100:101]
	v_pk_fma_f32 v[96:97], v[96:97], s[50:51], v[178:179] op_sel_hi:[1,0,0]
	s_nop 0
	v_mul_f32_e32 v102, 0x4b800000, v97
	v_mul_f32_e32 v103, 0x4b800000, v96
	v_cmp_gt_f32_e32 vcc, s29, v96
	v_cmp_gt_f32_e64 s[2:3], s29, v97
	s_nop 0
	v_cndmask_b32_e32 v101, v96, v103, vcc
	v_cndmask_b32_e64 v100, v97, v102, s[2:3]
	v_pk_fma_f32 v[96:97], v[98:99], s[50:51], v[178:179] op_sel_hi:[1,0,0]
	v_rsq_f32_e32 v98, v100
	v_rsq_f32_e32 v99, v101
	v_mul_f32_e32 v100, 0x4b800000, v97
	v_cmp_gt_f32_e64 s[6:7], s29, v97
	v_mul_f32_e32 v101, 0x4b800000, v96
	v_cmp_gt_f32_e64 s[4:5], s29, v96
	v_cndmask_b32_e64 v97, v97, v100, s[6:7]
	v_rsq_f32_e32 v97, v97
	v_cndmask_b32_e64 v96, v96, v101, s[4:5]
	v_rsq_f32_e32 v104, v96
	v_mul_f32_e32 v96, 0x45800000, v98
	v_mul_f32_e32 v100, 0x45800000, v99
	v_cndmask_b32_e64 v98, v98, v96, s[2:3]
	v_cndmask_b32_e32 v96, v99, v100, vcc
	v_pk_mul_f32 v[50:51], v[50:51], v[98:99] op_sel_hi:[1,0]
	v_pk_mul_f32 v[52:53], v[52:53], v[98:99] op_sel_hi:[1,0]
	v_pk_mul_f32 v[54:55], v[54:55], v[96:97] op_sel_hi:[1,0]
	v_pk_mul_f32 v[56:57], v[56:57], v[96:97] op_sel_hi:[1,0]
	v_mul_f32_e32 v99, 0x45800000, v97
	s_waitcnt vmcnt(0)
	v_pk_fma_f32 v[100:101], v[92:93], v[52:53], v[68:69]
	v_pk_fma_f32 v[56:57], v[92:93], v[56:57], v[68:69]
	v_pk_fma_f32 v[54:55], v[94:95], v[54:55], v[66:67]
	v_cndmask_b32_e64 v52, v97, v99, s[6:7]
	v_mul_f32_e32 v105, 0x45800000, v104
	v_pk_fma_f32 v[102:103], v[94:95], v[50:51], v[66:67]
	v_cvt_pk_bf16_f32 v54, v54, v55
	v_cvt_pk_bf16_f32 v55, v56, v57
	v_pk_mul_f32 v[56:57], v[58:59], v[52:53] op_sel_hi:[1,0]
	v_cndmask_b32_e64 v50, v104, v105, s[4:5]
	v_cvt_pk_bf16_f32 v102, v102, v103
	v_cvt_pk_bf16_f32 v103, v100, v101
	v_pk_mul_f32 v[58:59], v[60:61], v[52:53] op_sel_hi:[1,0]
	v_pk_fma_f32 v[56:57], v[94:95], v[56:57], v[66:67]
	v_pk_mul_f32 v[60:61], v[62:63], v[50:51] op_sel_hi:[1,0]
	v_pk_mul_f32 v[62:63], v[64:65], v[50:51] op_sel_hi:[1,0]
	global_store_dwordx2 v[86:87], v[102:103], off offset:-3584
	global_store_dwordx2 v[86:87], v[54:55], off offset:-1536
	v_pk_fma_f32 v[54:55], v[92:93], v[58:59], v[68:69]
	v_cvt_pk_bf16_f32 v56, v56, v57
	v_pk_fma_f32 v[58:59], v[92:93], v[62:63], v[68:69]
	v_cvt_pk_bf16_f32 v57, v54, v55
	v_pk_fma_f32 v[60:61], v[94:95], v[60:61], v[66:67]
	v_cvt_pk_bf16_f32 v55, v58, v59
	v_pk_mul_f32 v[34:35], v[34:35], v[98:99] op_sel_hi:[1,0]
	v_cvt_pk_bf16_f32 v54, v60, v61
	global_store_dwordx2 v[74:75], v[56:57], off offset:-3584
	global_store_dwordx2 v[74:75], v[54:55], off offset:-1536
	global_load_dwordx4 v[54:57], v[106:107], off
	s_nop 0
	global_load_dwordx4 v[58:61], v[88:89], off offset:1024
	global_load_dwordx4 v[62:65], v[72:73], off offset:1024
	v_pk_mul_f32 v[36:37], v[36:37], v[98:99] op_sel_hi:[1,0]
	v_pk_mul_f32 v[38:39], v[38:39], v[96:97] op_sel_hi:[1,0]
	v_pk_mul_f32 v[40:41], v[40:41], v[96:97] op_sel_hi:[1,0]
	v_pk_mul_f32 v[42:43], v[42:43], v[52:53] op_sel_hi:[1,0]
	v_pk_mul_f32 v[44:45], v[44:45], v[52:53] op_sel_hi:[1,0]
	v_pk_mul_f32 v[46:47], v[46:47], v[50:51] op_sel_hi:[1,0]
	v_pk_mul_f32 v[48:49], v[48:49], v[50:51] op_sel_hi:[1,0]
	v_lshl_add_u64 v[66:67], v[90:91], 0, v[82:83]
	v_pk_mul_f32 v[18:19], v[18:19], v[98:99] op_sel_hi:[1,0]
	v_pk_mul_f32 v[20:21], v[20:21], v[98:99] op_sel_hi:[1,0]
	v_pk_mul_f32 v[22:23], v[22:23], v[96:97] op_sel_hi:[1,0]
	v_pk_mul_f32 v[24:25], v[24:25], v[96:97] op_sel_hi:[1,0]
	v_pk_mul_f32 v[26:27], v[26:27], v[52:53] op_sel_hi:[1,0]
	v_pk_mul_f32 v[28:29], v[28:29], v[52:53] op_sel_hi:[1,0]
	v_pk_mul_f32 v[30:31], v[30:31], v[50:51] op_sel_hi:[1,0]
	v_pk_mul_f32 v[32:33], v[32:33], v[50:51] op_sel_hi:[1,0]
	v_pk_mul_f32 v[2:3], v[2:3], v[98:99] op_sel_hi:[1,0]
	v_pk_mul_f32 v[4:5], v[4:5], v[98:99] op_sel_hi:[1,0]
	v_pk_mul_f32 v[6:7], v[6:7], v[96:97] op_sel_hi:[1,0]
	v_pk_mul_f32 v[8:9], v[8:9], v[96:97] op_sel_hi:[1,0]
	v_cmp_lt_i32_e32 vcc, s44, v70
	v_pk_mul_f32 v[10:11], v[10:11], v[52:53] op_sel_hi:[1,0]
	v_pk_mul_f32 v[12:13], v[12:13], v[52:53] op_sel_hi:[1,0]
	v_pk_mul_f32 v[14:15], v[14:15], v[50:51] op_sel_hi:[1,0]
	v_pk_mul_f32 v[16:17], v[16:17], v[50:51] op_sel_hi:[1,0]
	s_or_b64 s[16:17], vcc, s[16:17]
	s_waitcnt vmcnt(2)
; __device__ __forceinline__ unsigned cvt_pk_bf16(float lo, float hi) { unsigned r; asm("v_cvt_pk_bf16_f32 %0, %1, %2" : "=v"(r) : "v"(lo), "v"(hi)); return r; }
; __device__ void norm_rows(const float* Xc, const float* Xl, bf16_t* H, const float* nw, const float* modl, int shi, int sci, int base, int r1, int step) {
;     ...
;         for (int q = 0; q < 4; ++q) { const int c = q * 256 + lane * 4;
;             const f32x4 w = *(const f32x4*)(nw + c), sh = *(const f32x4*)(shp + c), sc = *(const f32x4*)(scp + c);
;             const f32x4 wm = w * (sc + 1.0f);
; #pragma unroll
;             for (int u = 0; u < 4; ++u) { const float rstd = rsqrtf(ss[u] * (1.0f / 1024.0f) + 1e-6f);
;                 const f32x4 h = (v[u][q] * rstd) * wm + sh;
;                 u32x2 o; o.x = cvt_pk_bf16(h[0], h[1]); o.y = cvt_pk_bf16(h[2], h[3]);
;                 *(u32x2*)(H + (size_t)(row + u) * 1024 + c) = o; } }
	v_pk_add_f32 v[54:55], v[54:55], 1.0 op_sel_hi:[1,0]
	v_pk_add_f32 v[56:57], v[56:57], 1.0 op_sel_hi:[1,0]
	s_waitcnt vmcnt(0)
	v_pk_mul_f32 v[54:55], v[62:63], v[54:55]
	v_pk_mul_f32 v[56:57], v[64:65], v[56:57]
	v_pk_fma_f32 v[34:35], v[34:35], v[54:55], v[58:59]
	v_pk_fma_f32 v[36:37], v[36:37], v[56:57], v[60:61]
	v_pk_fma_f32 v[40:41], v[40:41], v[56:57], v[60:61]
	v_pk_fma_f32 v[38:39], v[38:39], v[54:55], v[58:59]
	v_cvt_pk_bf16_f32 v34, v34, v35
	v_cvt_pk_bf16_f32 v35, v36, v37
	v_pk_fma_f32 v[44:45], v[44:45], v[56:57], v[60:61]
	v_pk_fma_f32 v[42:43], v[42:43], v[54:55], v[58:59]
	v_pk_fma_f32 v[48:49], v[48:49], v[56:57], v[60:61]
	v_pk_fma_f32 v[46:47], v[46:47], v[54:55], v[58:59]
	v_cvt_pk_bf16_f32 v36, v38, v39
	v_cvt_pk_bf16_f32 v37, v40, v41
	v_cvt_pk_bf16_f32 v38, v42, v43
	v_cvt_pk_bf16_f32 v39, v44, v45
	v_cvt_pk_bf16_f32 v41, v48, v49
	s_nop 0
	v_cvt_pk_bf16_f32 v40, v46, v47
	global_store_dwordx2 v[86:87], v[34:35], off offset:-3072
	global_store_dwordx2 v[86:87], v[36:37], off offset:-1024
	global_store_dwordx2 v[74:75], v[38:39], off offset:-3072
	global_store_dwordx2 v[74:75], v[40:41], off offset:-1024
	global_load_dwordx4 v[34:37], v[66:67], off
	s_nop 0
	global_load_dwordx4 v[38:41], v[88:89], off offset:2048
	global_load_dwordx4 v[42:45], v[72:73], off offset:2048
	v_lshl_add_u64 v[46:47], v[90:91], 0, v[84:85]
	s_waitcnt vmcnt(2)
	v_pk_add_f32 v[34:35], v[34:35], 1.0 op_sel_hi:[1,0]
	v_pk_add_f32 v[36:37], v[36:37], 1.0 op_sel_hi:[1,0]
	s_waitcnt vmcnt(0)
	v_pk_mul_f32 v[34:35], v[42:43], v[34:35]
	v_pk_mul_f32 v[36:37], v[44:45], v[36:37]
	v_pk_fma_f32 v[18:19], v[18:19], v[34:35], v[38:39]
	v_pk_fma_f32 v[20:21], v[20:21], v[36:37], v[40:41]
	v_pk_fma_f32 v[24:25], v[24:25], v[36:37], v[40:41]
	v_pk_fma_f32 v[22:23], v[22:23], v[34:35], v[38:39]
	v_cvt_pk_bf16_f32 v18, v18, v19
	v_cvt_pk_bf16_f32 v19, v20, v21
	v_pk_fma_f32 v[28:29], v[28:29], v[36:37], v[40:41]
	v_pk_fma_f32 v[26:27], v[26:27], v[34:35], v[38:39]
	v_pk_fma_f32 v[32:33], v[32:33], v[36:37], v[40:41]
	v_pk_fma_f32 v[30:31], v[30:31], v[34:35], v[38:39]
	v_cvt_pk_bf16_f32 v20, v22, v23
	v_cvt_pk_bf16_f32 v21, v24, v25
	v_cvt_pk_bf16_f32 v22, v26, v27
	v_cvt_pk_bf16_f32 v23, v28, v29
	v_cvt_pk_bf16_f32 v25, v32, v33
	s_nop 0
	v_cvt_pk_bf16_f32 v24, v30, v31
	global_store_dwordx2 v[86:87], v[18:19], off offset:-2560
	global_store_dwordx2 v[86:87], v[20:21], off offset:-512
	global_store_dwordx2 v[74:75], v[22:23], off offset:-2560
	global_store_dwordx2 v[74:75], v[24:25], off offset:-512
	global_load_dwordx4 v[18:21], v[46:47], off
	s_nop 0
	global_load_dwordx4 v[22:25], v[88:89], off offset:3072
	global_load_dwordx4 v[26:29], v[72:73], off offset:3072
	s_waitcnt vmcnt(2)
	v_pk_add_f32 v[18:19], v[18:19], 1.0 op_sel_hi:[1,0]
	v_pk_add_f32 v[20:21], v[20:21], 1.0 op_sel_hi:[1,0]
	s_waitcnt vmcnt(0)
	v_pk_mul_f32 v[18:19], v[26:27], v[18:19]
	v_pk_mul_f32 v[20:21], v[28:29], v[20:21]
	v_pk_fma_f32 v[2:3], v[2:3], v[18:19], v[22:23]
	v_pk_fma_f32 v[4:5], v[4:5], v[20:21], v[24:25]
	v_pk_fma_f32 v[8:9], v[8:9], v[20:21], v[24:25]
	v_pk_fma_f32 v[6:7], v[6:7], v[18:19], v[22:23]
	v_cvt_pk_bf16_f32 v2, v2, v3
	v_cvt_pk_bf16_f32 v3, v4, v5
	v_pk_fma_f32 v[12:13], v[12:13], v[20:21], v[24:25]
	v_pk_fma_f32 v[10:11], v[10:11], v[18:19], v[22:23]
	v_pk_fma_f32 v[16:17], v[16:17], v[20:21], v[24:25]
	v_pk_fma_f32 v[14:15], v[14:15], v[18:19], v[22:23]
	v_cvt_pk_bf16_f32 v4, v6, v7
	v_cvt_pk_bf16_f32 v5, v8, v9
	v_cvt_pk_bf16_f32 v6, v10, v11
	v_cvt_pk_bf16_f32 v7, v12, v13
	v_cvt_pk_bf16_f32 v9, v16, v17
	s_nop 0
	v_cvt_pk_bf16_f32 v8, v14, v15
	global_store_dwordx2 v[86:87], v[2:3], off offset:-2048
	global_store_dwordx2 v[74:75], v[4:5], off offset:-4096
	global_store_dwordx2 v[74:75], v[6:7], off offset:-2048
	global_store_dwordx2 v[74:75], v[8:9], off
	v_lshl_add_u64 v[74:75], v[74:75], 0, s[92:93]
	s_andn2_b64 exec, exec, s[16:17]
	s_cbranch_execnz .LBB0_113

; __device__ void norm_rows(const float* Xc, const float* Xl, bf16_t* H, const float* nw, const float* modl, int shi, int sci, int base, int r1, int step) {
;     ...
;     for (int row = base + wid * 4; row < r1; row += step) {
;         const float* xp = (row < TCTX ? Xc : Xl) + (size_t)row * 1024 + lane * 4;
;         f32x4 v[4][4]; float ss[4];
; #pragma unroll
;         for (int u = 0; u < 4; ++u)
; #pragma unroll
;             for (int q = 0; q < 4; ++q) v[u][q] = *(const f32x4*)(xp + u * 1024 + q * 256);
; #pragma unroll
;         for (int u = 0; u < 4; ++u) { float a = 0.f;
; #pragma unroll
;             for (int q = 0; q < 4; ++q) a += v[u][q][0] * v[u][q][0] + v[u][q][1] * v[u][q][1] + v[u][q][2] * v[u][q][2] + v[u][q][3] * v[u][q][3];
;             ss[u] = a; }
; #pragma unroll
;         for (int o = 32; o >= 1; o >>= 1)
; #pragma unroll
;             for (int u = 0; u < 4; ++u) ss[u] += __int_as_float(__builtin_amdgcn_ds_bpermute((lane ^ o) << 2, __float_as_int(ss[u])));
;         const int mb = row < TCTX ? 32 : (row - TCTX) >> 11;
.LBB0_509:
	global_load_dwordx4 v[62:65], v[76:77], off nt
	global_load_dwordx4 v[34:37], v[76:77], off offset:1024 nt
	global_load_dwordx4 v[18:21], v[76:77], off offset:2048 nt
	global_load_dwordx4 v[2:5], v[76:77], off offset:3072 nt
	v_add_co_u32_e32 v6, vcc, 0x1000, v76
	s_mov_b64 s[0:1], 0x3000
	s_nop 0
	v_addc_co_u32_e32 v7, vcc, 0, v77, vcc
	global_load_dwordx4 v[58:61], v[6:7], off nt
	global_load_dwordx4 v[38:41], v[6:7], off offset:1024 nt
	global_load_dwordx4 v[22:25], v[6:7], off offset:2048 nt
	s_nop 0
	global_load_dwordx4 v[6:9], v[6:7], off offset:3072 nt
	v_add_co_u32_e32 v10, vcc, s71, v76
	v_mov_b32_e32 v79, v0
	s_nop 0
	v_addc_co_u32_e32 v11, vcc, 0, v77, vcc
	v_add_co_u32_e32 v12, vcc, s11, v76
	v_mov_b32_e32 v81, v0
	s_nop 0
	v_addc_co_u32_e32 v13, vcc, 0, v77, vcc
	global_load_dwordx4 v[54:57], v[12:13], off offset:-4096 nt
	global_load_dwordx4 v[46:49], v[10:11], off offset:1024 nt
	global_load_dwordx4 v[30:33], v[10:11], off offset:2048 nt
	global_load_dwordx4 v[14:17], v[10:11], off offset:3072 nt
	global_load_dwordx4 v[50:53], v[12:13], off nt
	global_load_dwordx4 v[42:45], v[12:13], off offset:1024 nt
	global_load_dwordx4 v[26:29], v[12:13], off offset:2048 nt
	s_nop 0
	global_load_dwordx4 v[10:13], v[12:13], off offset:3072 nt
	v_cmp_lt_i32_e32 vcc, s31, v70
	global_load_dwordx4 v[116:119], v[72:73], off
	v_mov_b32_e32 v83, v0
	v_mov_b32_e32 v85, v0
	v_lshl_add_u64 v[76:77], v[76:77], 0, s[8:9]
	s_waitcnt vmcnt(16)
	v_mov_b32_e32 v68, v63
	s_waitcnt vmcnt(15)
	v_mov_b32_e32 v69, v35
	v_mov_b32_e32 v66, v62
	v_mov_b32_e32 v67, v34
	v_pk_mul_f32 v[68:69], v[68:69], v[68:69]
	s_nop 0
	v_pk_fma_f32 v[66:67], v[66:67], v[66:67], v[68:69]
	v_mov_b32_e32 v68, v64
	v_mov_b32_e32 v69, v36
	v_pk_fma_f32 v[66:67], v[68:69], v[68:69], v[66:67]
	v_mov_b32_e32 v68, v65
	v_mov_b32_e32 v69, v37
	v_pk_fma_f32 v[90:91], v[68:69], v[68:69], v[66:67]
	s_waitcnt vmcnt(14)
	v_mov_b32_e32 v68, v19
	s_waitcnt vmcnt(13)
	v_mov_b32_e32 v69, v3
	v_mov_b32_e32 v66, v18
	v_mov_b32_e32 v67, v2
	v_pk_mul_f32 v[68:69], v[68:69], v[68:69]
	s_nop 0
	v_pk_fma_f32 v[66:67], v[66:67], v[66:67], v[68:69]
	v_mov_b32_e32 v68, v20
	v_mov_b32_e32 v69, v4
	v_pk_fma_f32 v[66:67], v[68:69], v[68:69], v[66:67]
	v_mov_b32_e32 v68, v21
	v_mov_b32_e32 v69, v5
	v_pk_fma_f32 v[100:101], v[68:69], v[68:69], v[66:67]
	s_waitcnt vmcnt(12)
	v_mov_b32_e32 v68, v59
	s_waitcnt vmcnt(11)
	v_mov_b32_e32 v69, v39
	v_mov_b32_e32 v66, v58
	v_mov_b32_e32 v67, v38
	v_pk_mul_f32 v[68:69], v[68:69], v[68:69]
	s_nop 0
	v_pk_fma_f32 v[66:67], v[66:67], v[66:67], v[68:69]
	v_mov_b32_e32 v68, v60
	v_mov_b32_e32 v69, v40
	v_pk_fma_f32 v[66:67], v[68:69], v[68:69], v[66:67]
	v_mov_b32_e32 v68, v61
	v_mov_b32_e32 v69, v41
	v_pk_fma_f32 v[102:103], v[68:69], v[68:69], v[66:67]
	s_waitcnt vmcnt(10)
	v_mov_b32_e32 v68, v23
	s_waitcnt vmcnt(9)
	v_mov_b32_e32 v69, v7
	v_mov_b32_e32 v66, v22
	v_mov_b32_e32 v67, v6
	v_pk_mul_f32 v[68:69], v[68:69], v[68:69]
	s_nop 0
	v_pk_fma_f32 v[66:67], v[66:67], v[66:67], v[68:69]
	v_mov_b32_e32 v68, v24
	v_mov_b32_e32 v69, v8
	v_pk_fma_f32 v[66:67], v[68:69], v[68:69], v[66:67]
	v_mov_b32_e32 v68, v25
	v_mov_b32_e32 v69, v9
	v_pk_fma_f32 v[104:105], v[68:69], v[68:69], v[66:67]
	s_waitcnt vmcnt(8)
	v_mov_b32_e32 v68, v55
	s_waitcnt vmcnt(7)
	v_mov_b32_e32 v69, v47
	v_mov_b32_e32 v66, v54
	v_mov_b32_e32 v67, v46
	v_pk_mul_f32 v[68:69], v[68:69], v[68:69]
	s_nop 0
	v_pk_fma_f32 v[66:67], v[66:67], v[66:67], v[68:69]
	v_mov_b32_e32 v68, v56
	v_mov_b32_e32 v69, v48
	v_pk_fma_f32 v[66:67], v[68:69], v[68:69], v[66:67]
	v_mov_b32_e32 v68, v57
	v_mov_b32_e32 v69, v49
	v_pk_fma_f32 v[92:93], v[68:69], v[68:69], v[66:67]
	s_waitcnt vmcnt(6)
	v_mov_b32_e32 v68, v31
	s_waitcnt vmcnt(5)
	v_mov_b32_e32 v69, v15
	v_mov_b32_e32 v66, v30
	v_mov_b32_e32 v67, v14
	v_pk_mul_f32 v[68:69], v[68:69], v[68:69]
	s_nop 0
	v_pk_fma_f32 v[66:67], v[66:67], v[66:67], v[68:69]
	v_mov_b32_e32 v68, v32
	v_mov_b32_e32 v69, v16
	v_pk_fma_f32 v[66:67], v[68:69], v[68:69], v[66:67]
	v_mov_b32_e32 v68, v33
	v_mov_b32_e32 v69, v17
	v_pk_fma_f32 v[94:95], v[68:69], v[68:69], v[66:67]
	s_waitcnt vmcnt(4)
	v_mov_b32_e32 v68, v51
	s_waitcnt vmcnt(3)
	v_mov_b32_e32 v69, v43
	v_mov_b32_e32 v66, v50
	v_mov_b32_e32 v67, v42
	v_pk_mul_f32 v[68:69], v[68:69], v[68:69]
	s_nop 0
	v_pk_fma_f32 v[66:67], v[66:67], v[66:67], v[68:69]
	v_mov_b32_e32 v68, v52
	v_mov_b32_e32 v69, v44
	v_pk_fma_f32 v[66:67], v[68:69], v[68:69], v[66:67]
	v_mov_b32_e32 v68, v53
	v_mov_b32_e32 v69, v45
	v_pk_fma_f32 v[96:97], v[68:69], v[68:69], v[66:67]
	s_waitcnt vmcnt(2)
	v_mov_b32_e32 v68, v27
	s_waitcnt vmcnt(1)
	v_mov_b32_e32 v69, v11
	v_mov_b32_e32 v66, v26
	v_mov_b32_e32 v67, v10
	v_pk_mul_f32 v[68:69], v[68:69], v[68:69]
	s_nop 0
	v_pk_fma_f32 v[66:67], v[66:67], v[66:67], v[68:69]
	v_mov_b32_e32 v68, v28
	v_mov_b32_e32 v69, v12
	v_pk_fma_f32 v[66:67], v[68:69], v[68:69], v[66:67]
	v_mov_b32_e32 v68, v29
	v_mov_b32_e32 v69, v13
	v_pk_fma_f32 v[98:99], v[68:69], v[68:69], v[66:67]
	v_add_u32_e32 v66, 0xffffe000, v70
	v_ashrrev_i32_e32 v66, 11, v66
	v_mul_i32_i24_e32 v66, 6, v66
	v_cndmask_b32_e32 v66, v211, v66, vcc
	v_ashrrev_i32_e32 v67, 31, v66
	v_lshlrev_b64 v[66:67], 12, v[66:67]
	v_lshl_add_u64 v[66:67], s[52:53], 0, v[66:67]
	v_lshl_add_u64 v[88:89], v[66:67], 0, s[0:1]
	s_mov_b64 s[0:1], 0x4000
	v_lshl_add_u64 v[86:87], v[66:67], 0, s[0:1]
	v_lshl_add_u64 v[106:107], v[86:87], 0, v[78:79]
	global_load_dwordx4 v[106:109], v[106:107], off
	v_lshl_add_u64 v[66:67], v[88:89], 0, v[78:79]
	global_load_dwordx4 v[66:69], v[66:67], off
	v_add_u32_e32 v70, s70, v70
	s_waitcnt vmcnt(1)
; __device__ __forceinline__ unsigned cvt_pk_bf16(float lo, float hi) { unsigned r; asm("v_cvt_pk_bf16_f32 %0, %1, %2" : "=v"(r) : "v"(lo), "v"(hi)); return r; }
; __device__ void norm_rows(const float* Xc, const float* Xl, bf16_t* H, const float* nw, const float* modl, int shi, int sci, int base, int r1, int step) {
;     ...
;         for (int o = 32; o >= 1; o >>= 1)
; #pragma unroll
;             for (int u = 0; u < 4; ++u) ss[u] += __int_as_float(__builtin_amdgcn_ds_bpermute((lane ^ o) << 2, __float_as_int(ss[u])));
;         const int mb = row < TCTX ? 32 : (row - TCTX) >> 11;
;         const float* shp = modl + ((size_t)mb * 6 + shi) * 1024; const float* scp = modl + ((size_t)mb * 6 + sci) * 1024;
; #pragma unroll
;         for (int q = 0; q < 4; ++q) { const int c = q * 256 + lane * 4;
;             const f32x4 w = *(const f32x4*)(nw + c), sh = *(const f32x4*)(shp + c), sc = *(const f32x4*)(scp + c);
;             const f32x4 wm = w * (sc + 1.0f);
; #pragma unroll
;             for (int u = 0; u < 4; ++u) { const float rstd = rsqrtf(ss[u] * (1.0f / 1024.0f) + 1e-6f);
;                 const f32x4 h = (v[u][q] * rstd) * wm + sh;
;                 u32x2 o; o.x = cvt_pk_bf16(h[0], h[1]); o.y = cvt_pk_bf16(h[2], h[3]);
;                 *(u32x2*)(H + (size_t)(row + u) * 1024 + c) = o; } }
	v_pk_add_f32 v[108:109], v[108:109], 1.0 op_sel_hi:[1,0]
	v_pk_add_f32 v[120:121], v[106:107], 1.0 op_sel_hi:[1,0]
	v_pk_mul_f32 v[106:107], v[118:119], v[108:109]
	v_pk_mul_f32 v[108:109], v[116:117], v[120:121]
	v_mov_b32_e32 v116, v102
	v_mov_b32_e32 v117, v90
	v_mov_b32_e32 v90, v103
	v_pk_add_f32 v[90:91], v[116:117], v[90:91]
	v_mov_b32_e32 v102, v104
	v_mov_b32_e32 v103, v100
	v_pk_add_f32 v[90:91], v[90:91], v[102:103]
	v_mov_b32_e32 v100, v105
	v_pk_add_f32 v[90:91], v[90:91], v[100:101]
	ds_bpermute_b32 v101, v1, v91
	ds_bpermute_b32 v100, v1, v90
	s_waitcnt lgkmcnt(0)
	v_pk_add_f32 v[90:91], v[90:91], v[100:101]
	ds_bpermute_b32 v101, v110, v91
	ds_bpermute_b32 v100, v110, v90
	s_waitcnt lgkmcnt(0)
	v_pk_add_f32 v[90:91], v[90:91], v[100:101]
	ds_bpermute_b32 v101, v111, v91
	ds_bpermute_b32 v100, v111, v90
	s_waitcnt lgkmcnt(0)
	v_pk_add_f32 v[90:91], v[90:91], v[100:101]
	ds_bpermute_b32 v101, v112, v91
	ds_bpermute_b32 v100, v112, v90
	s_waitcnt lgkmcnt(0)
	v_pk_add_f32 v[90:91], v[90:91], v[100:101]
	ds_bpermute_b32 v101, v113, v91
	ds_bpermute_b32 v100, v113, v90
	s_waitcnt lgkmcnt(0)
	v_pk_add_f32 v[90:91], v[90:91], v[100:101]
	ds_bpermute_b32 v101, v114, v91
	ds_bpermute_b32 v100, v114, v90
	s_waitcnt lgkmcnt(0)
	v_pk_add_f32 v[90:91], v[90:91], v[100:101]
	v_mov_b64_e32 v[100:101], s[28:29]
	v_pk_fma_f32 v[102:103], v[90:91], s[44:45], v[100:101] op_sel_hi:[1,0,0]
	s_nop 0
	v_mul_f32_e32 v71, 0x4b800000, v103
	v_cmp_gt_f32_e64 s[2:3], s29, v103
	v_cmp_gt_f32_e32 vcc, s29, v102
	s_nop 0
	v_cndmask_b32_e64 v71, v103, v71, s[2:3]
	v_rsq_f32_e32 v71, v71
	s_nop 0
	v_mul_f32_e32 v79, 0x45800000, v71
	v_cndmask_b32_e64 v90, v71, v79, s[2:3]
	v_pk_mul_f32 v[64:65], v[64:65], v[90:91] op_sel_hi:[1,0]
	v_pk_mul_f32 v[62:63], v[62:63], v[90:91] op_sel_hi:[1,0]
	s_waitcnt vmcnt(0)
	v_pk_fma_f32 v[64:65], v[106:107], v[64:65], v[68:69]
	v_pk_fma_f32 v[62:63], v[108:109], v[62:63], v[66:67]
	v_cvt_pk_bf16_f32 v105, v64, v65
	v_mul_f32_e32 v64, 0x4b800000, v102
	v_cndmask_b32_e32 v64, v102, v64, vcc
	v_rsq_f32_e32 v64, v64
	v_cvt_pk_bf16_f32 v104, v62, v63
	v_add_co_u32_e64 v62, s[2:3], s36, v74
	v_mul_f32_e32 v65, 0x45800000, v64
	v_cndmask_b32_e32 v64, v64, v65, vcc
	v_pk_mul_f32 v[58:59], v[58:59], v[64:65] op_sel_hi:[1,0]
	v_pk_mul_f32 v[60:61], v[60:61], v[64:65] op_sel_hi:[1,0]
	v_pk_fma_f32 v[58:59], v[108:109], v[58:59], v[66:67]
	v_addc_co_u32_e64 v63, s[2:3], -1, v75, s[2:3]
	v_pk_fma_f32 v[60:61], v[106:107], v[60:61], v[68:69]
	v_cvt_pk_bf16_f32 v58, v58, v59
	global_store_dwordx2 v[62:63], v[104:105], off offset:-3584
	v_cvt_pk_bf16_f32 v59, v60, v61
	global_store_dwordx2 v[62:63], v[58:59], off offset:-1536
	v_mov_b32_e32 v58, v96
	v_mov_b32_e32 v59, v92
	v_mov_b32_e32 v92, v97
	v_pk_add_f32 v[58:59], v[58:59], v[92:93]
	v_mov_b32_e32 v60, v98
	v_mov_b32_e32 v61, v94
	v_pk_add_f32 v[58:59], v[58:59], v[60:61]
	v_mov_b32_e32 v94, v99
	v_pk_add_f32 v[58:59], v[58:59], v[94:95]
	ds_bpermute_b32 v61, v1, v59
	ds_bpermute_b32 v60, v1, v58
	v_pk_mul_f32 v[34:35], v[34:35], v[90:91] op_sel_hi:[1,0]
	v_pk_mul_f32 v[36:37], v[36:37], v[90:91] op_sel_hi:[1,0]
	v_pk_mul_f32 v[18:19], v[18:19], v[90:91] op_sel_hi:[1,0]
	v_pk_mul_f32 v[20:21], v[20:21], v[90:91] op_sel_hi:[1,0]
	s_waitcnt lgkmcnt(0)
	v_pk_add_f32 v[58:59], v[58:59], v[60:61]
	ds_bpermute_b32 v61, v110, v59
	ds_bpermute_b32 v60, v110, v58
	v_pk_mul_f32 v[2:3], v[2:3], v[90:91] op_sel_hi:[1,0]
	v_pk_mul_f32 v[4:5], v[4:5], v[90:91] op_sel_hi:[1,0]
	s_waitcnt lgkmcnt(0)
	v_pk_add_f32 v[58:59], v[58:59], v[60:61]
	ds_bpermute_b32 v61, v111, v59
	ds_bpermute_b32 v60, v111, v58
	s_waitcnt lgkmcnt(0)
	v_pk_add_f32 v[58:59], v[58:59], v[60:61]
	ds_bpermute_b32 v61, v112, v59
	ds_bpermute_b32 v60, v112, v58
	s_waitcnt lgkmcnt(0)
	v_pk_add_f32 v[58:59], v[58:59], v[60:61]
	ds_bpermute_b32 v61, v113, v59
	ds_bpermute_b32 v60, v113, v58
	s_waitcnt lgkmcnt(0)
	v_pk_add_f32 v[58:59], v[58:59], v[60:61]
	ds_bpermute_b32 v61, v114, v59
	ds_bpermute_b32 v60, v114, v58
	s_waitcnt lgkmcnt(0)
	v_pk_add_f32 v[58:59], v[58:59], v[60:61]
	s_nop 0
	v_pk_fma_f32 v[60:61], v[58:59], s[44:45], v[100:101] op_sel_hi:[1,0,0]
	s_nop 0
	v_mul_f32_e32 v58, 0x4b800000, v61
	v_cmp_gt_f32_e64 s[2:3], s29, v61
	v_cmp_gt_f32_e32 vcc, s29, v60
	s_nop 0
	v_cndmask_b32_e64 v58, v61, v58, s[2:3]
	v_rsq_f32_e32 v58, v58
	s_nop 0
	v_mul_f32_e32 v59, 0x45800000, v58
	v_cndmask_b32_e64 v58, v58, v59, s[2:3]
	v_pk_mul_f32 v[54:55], v[54:55], v[58:59] op_sel_hi:[1,0]
	v_pk_mul_f32 v[56:57], v[56:57], v[58:59] op_sel_hi:[1,0]
	v_pk_fma_f32 v[54:55], v[108:109], v[54:55], v[66:67]
	v_pk_fma_f32 v[56:57], v[106:107], v[56:57], v[68:69]
	v_cvt_pk_bf16_f32 v54, v54, v55
	s_nop 0
	v_cvt_pk_bf16_f32 v55, v56, v57
	global_store_dwordx2 v[74:75], v[54:55], off offset:-3584
	v_mul_f32_e32 v54, 0x4b800000, v60
	v_cndmask_b32_e32 v54, v60, v54, vcc
	v_rsq_f32_e32 v54, v54
	s_nop 0
	v_mul_f32_e32 v55, 0x45800000, v54
	v_cndmask_b32_e32 v60, v54, v55, vcc
	v_pk_mul_f32 v[50:51], v[50:51], v[60:61] op_sel_hi:[1,0]
	v_pk_mul_f32 v[52:53], v[52:53], v[60:61] op_sel_hi:[1,0]
	v_pk_fma_f32 v[50:51], v[108:109], v[50:51], v[66:67]
	v_pk_fma_f32 v[52:53], v[106:107], v[52:53], v[68:69]
	v_cvt_pk_bf16_f32 v50, v50, v51
	v_lshl_add_u64 v[54:55], v[88:89], 0, v[80:81]
	v_cvt_pk_bf16_f32 v51, v52, v53
	global_store_dwordx2 v[74:75], v[50:51], off offset:-1536
	v_lshl_add_u64 v[66:67], v[86:87], 0, v[80:81]
	global_load_dwordx4 v[54:57], v[54:55], off
	v_cmp_lt_i32_e32 vcc, s30, v70
	global_load_dwordx4 v[66:69], v[66:67], off
	s_or_b64 s[6:7], vcc, s[6:7]
	global_load_dwordx4 v[50:53], v[72:73], off offset:1024
	s_waitcnt vmcnt(1)
; __device__ __forceinline__ unsigned cvt_pk_bf16(float lo, float hi) { unsigned r; asm("v_cvt_pk_bf16_f32 %0, %1, %2" : "=v"(r) : "v"(lo), "v"(hi)); return r; }
; __device__ void norm_rows(const float* Xc, const float* Xl, bf16_t* H, const float* nw, const float* modl, int shi, int sci, int base, int r1, int step) {
;     ...
;         for (int q = 0; q < 4; ++q) { const int c = q * 256 + lane * 4;
;             const f32x4 w = *(const f32x4*)(nw + c), sh = *(const f32x4*)(shp + c), sc = *(const f32x4*)(scp + c);
;             const f32x4 wm = w * (sc + 1.0f);
; #pragma unroll
;             for (int u = 0; u < 4; ++u) { const float rstd = rsqrtf(ss[u] * (1.0f / 1024.0f) + 1e-6f);
;                 const f32x4 h = (v[u][q] * rstd) * wm + sh;
;                 u32x2 o; o.x = cvt_pk_bf16(h[0], h[1]); o.y = cvt_pk_bf16(h[2], h[3]);
;                 *(u32x2*)(H + (size_t)(row + u) * 1024 + c) = o; } }
	v_pk_add_f32 v[66:67], v[66:67], 1.0 op_sel_hi:[1,0]
	v_pk_add_f32 v[68:69], v[68:69], 1.0 op_sel_hi:[1,0]
	s_waitcnt vmcnt(0)
	v_pk_mul_f32 v[50:51], v[50:51], v[66:67]
	v_pk_mul_f32 v[52:53], v[52:53], v[68:69]
	v_pk_fma_f32 v[34:35], v[34:35], v[50:51], v[54:55]
	v_pk_fma_f32 v[36:37], v[36:37], v[52:53], v[56:57]
	v_cvt_pk_bf16_f32 v34, v34, v35
	s_nop 0
	v_cvt_pk_bf16_f32 v35, v36, v37
	global_store_dwordx2 v[62:63], v[34:35], off offset:-3072
	v_pk_mul_f32 v[34:35], v[38:39], v[64:65] op_sel_hi:[1,0]
	v_pk_mul_f32 v[36:37], v[40:41], v[64:65] op_sel_hi:[1,0]
	v_pk_fma_f32 v[34:35], v[34:35], v[50:51], v[54:55]
	v_pk_fma_f32 v[36:37], v[36:37], v[52:53], v[56:57]
	v_cvt_pk_bf16_f32 v34, v34, v35
	v_lshl_add_u64 v[38:39], v[88:89], 0, v[82:83]
	v_cvt_pk_bf16_f32 v35, v36, v37
	global_store_dwordx2 v[62:63], v[34:35], off offset:-1024
	v_pk_mul_f32 v[34:35], v[46:47], v[58:59] op_sel_hi:[1,0]
	v_pk_mul_f32 v[36:37], v[48:49], v[58:59] op_sel_hi:[1,0]
	v_pk_fma_f32 v[34:35], v[34:35], v[50:51], v[54:55]
	v_pk_fma_f32 v[36:37], v[36:37], v[52:53], v[56:57]
	v_cvt_pk_bf16_f32 v34, v34, v35
	s_nop 0
	v_cvt_pk_bf16_f32 v35, v36, v37
	global_store_dwordx2 v[74:75], v[34:35], off offset:-3072
	v_pk_mul_f32 v[34:35], v[42:43], v[60:61] op_sel_hi:[1,0]
	v_pk_mul_f32 v[36:37], v[44:45], v[60:61] op_sel_hi:[1,0]
	v_pk_fma_f32 v[34:35], v[34:35], v[50:51], v[54:55]
	v_pk_fma_f32 v[36:37], v[36:37], v[52:53], v[56:57]
	v_cvt_pk_bf16_f32 v34, v34, v35
	v_lshl_add_u64 v[42:43], v[86:87], 0, v[82:83]
	v_cvt_pk_bf16_f32 v35, v36, v37
	global_store_dwordx2 v[74:75], v[34:35], off offset:-1024
	global_load_dwordx4 v[38:41], v[38:39], off
	s_nop 0
	global_load_dwordx4 v[42:45], v[42:43], off
	s_waitcnt vmcnt(0)
	v_pk_add_f32 v[42:43], v[42:43], 1.0 op_sel_hi:[1,0]
	global_load_dwordx4 v[34:37], v[72:73], off offset:2048
	v_pk_add_f32 v[44:45], v[44:45], 1.0 op_sel_hi:[1,0]
	s_waitcnt vmcnt(0)
	v_pk_mul_f32 v[34:35], v[34:35], v[42:43]
	v_pk_mul_f32 v[36:37], v[36:37], v[44:45]
	v_pk_fma_f32 v[18:19], v[18:19], v[34:35], v[38:39]
	v_pk_fma_f32 v[20:21], v[20:21], v[36:37], v[40:41]
	v_cvt_pk_bf16_f32 v18, v18, v19
	s_nop 0
	v_cvt_pk_bf16_f32 v19, v20, v21
	global_store_dwordx2 v[62:63], v[18:19], off offset:-2560
	v_pk_mul_f32 v[18:19], v[22:23], v[64:65] op_sel_hi:[1,0]
	v_pk_mul_f32 v[20:21], v[24:25], v[64:65] op_sel_hi:[1,0]
	v_pk_fma_f32 v[18:19], v[18:19], v[34:35], v[38:39]
	v_pk_fma_f32 v[20:21], v[20:21], v[36:37], v[40:41]
	v_cvt_pk_bf16_f32 v18, v18, v19
	v_lshl_add_u64 v[22:23], v[88:89], 0, v[84:85]
	v_cvt_pk_bf16_f32 v19, v20, v21
	global_store_dwordx2 v[62:63], v[18:19], off offset:-512
	v_pk_mul_f32 v[18:19], v[30:31], v[58:59] op_sel_hi:[1,0]
	v_pk_mul_f32 v[20:21], v[32:33], v[58:59] op_sel_hi:[1,0]
	v_pk_fma_f32 v[18:19], v[18:19], v[34:35], v[38:39]
	v_pk_fma_f32 v[20:21], v[20:21], v[36:37], v[40:41]
	v_cvt_pk_bf16_f32 v18, v18, v19
	s_nop 0
	v_cvt_pk_bf16_f32 v19, v20, v21
	global_store_dwordx2 v[74:75], v[18:19], off offset:-2560
	v_pk_mul_f32 v[18:19], v[26:27], v[60:61] op_sel_hi:[1,0]
	v_pk_mul_f32 v[20:21], v[28:29], v[60:61] op_sel_hi:[1,0]
	v_pk_fma_f32 v[18:19], v[18:19], v[34:35], v[38:39]
	v_pk_fma_f32 v[20:21], v[20:21], v[36:37], v[40:41]
	v_cvt_pk_bf16_f32 v18, v18, v19
	v_lshl_add_u64 v[26:27], v[86:87], 0, v[84:85]
	v_cvt_pk_bf16_f32 v19, v20, v21
	global_store_dwordx2 v[74:75], v[18:19], off offset:-512
	global_load_dwordx4 v[22:25], v[22:23], off
	s_nop 0
	global_load_dwordx4 v[26:29], v[26:27], off
	s_waitcnt vmcnt(0)
	v_pk_add_f32 v[26:27], v[26:27], 1.0 op_sel_hi:[1,0]
	global_load_dwordx4 v[18:21], v[72:73], off offset:3072
	v_pk_add_f32 v[28:29], v[28:29], 1.0 op_sel_hi:[1,0]
	s_waitcnt vmcnt(0)
	v_pk_mul_f32 v[18:19], v[18:19], v[26:27]
	v_pk_mul_f32 v[20:21], v[20:21], v[28:29]
	v_pk_fma_f32 v[2:3], v[2:3], v[18:19], v[22:23]
	v_pk_fma_f32 v[4:5], v[4:5], v[20:21], v[24:25]
	v_cvt_pk_bf16_f32 v2, v2, v3
	s_nop 0
	v_cvt_pk_bf16_f32 v3, v4, v5
	global_store_dwordx2 v[62:63], v[2:3], off offset:-2048
	v_pk_mul_f32 v[2:3], v[6:7], v[64:65] op_sel_hi:[1,0]
	v_pk_mul_f32 v[4:5], v[8:9], v[64:65] op_sel_hi:[1,0]
	v_pk_fma_f32 v[2:3], v[2:3], v[18:19], v[22:23]
	v_pk_fma_f32 v[4:5], v[4:5], v[20:21], v[24:25]
	v_cvt_pk_bf16_f32 v2, v2, v3
	s_nop 0
	v_cvt_pk_bf16_f32 v3, v4, v5
	global_store_dwordx2 v[74:75], v[2:3], off offset:-4096
	v_pk_mul_f32 v[2:3], v[14:15], v[58:59] op_sel_hi:[1,0]
	v_pk_mul_f32 v[4:5], v[16:17], v[58:59] op_sel_hi:[1,0]
	v_pk_fma_f32 v[2:3], v[2:3], v[18:19], v[22:23]
	v_pk_fma_f32 v[4:5], v[4:5], v[20:21], v[24:25]
	v_cvt_pk_bf16_f32 v2, v2, v3
	s_nop 0
	v_cvt_pk_bf16_f32 v3, v4, v5
	global_store_dwordx2 v[74:75], v[2:3], off offset:-2048
	v_pk_mul_f32 v[2:3], v[10:11], v[60:61] op_sel_hi:[1,0]
	v_pk_mul_f32 v[4:5], v[12:13], v[60:61] op_sel_hi:[1,0]
	v_pk_fma_f32 v[2:3], v[2:3], v[18:19], v[22:23]
	v_pk_fma_f32 v[4:5], v[4:5], v[20:21], v[24:25]
	v_cvt_pk_bf16_f32 v2, v2, v3
	s_nop 0
	v_cvt_pk_bf16_f32 v3, v4, v5
	global_store_dwordx2 v[74:75], v[2:3], off
	v_lshl_add_u64 v[74:75], v[74:75], 0, s[92:93]
	s_andn2_b64 exec, exec, s[6:7]
	s_cbranch_execnz .LBB0_509
